# gemm1 K-loop LDS-DMA loads bypass the vector L1 (sc1); co-resident workgroups drift apart there so L1 gives no sharing
# speedup vs baseline: 1.0108x; 1.0108x over previous
; DEV f32x4 mma_step(bf16x8 a, bf16x8 b, f32x4 c) { return MFMA(a, b, c); }
; template <class FragT, class AccT>
; DEV void gemm_core_t(const char* __restrict__ A, size_t lda_bytes, const char* __restrict__ Bt, size_t ldb_bytes, int kbytes,
;                      int m0, int n0, int Sshift, int dl, char* smem, AccT (&acc)[4][4]) {
;     ...
;   for (int kt = 0; kt < nk; ++kt) {
;     const unsigned so = (unsigned)(kt & 1) * 32768u;
;     char* nxt = smem + ((kt + 1) & 1) * 32768;
;     if (kt + 1 < nk) {
; #pragma unroll
;       for (int u = 0; u < 4; ++u) {
;         __builtin_amdgcn_global_load_lds((const unsigned*)(ap[u] + (size_t)(kt + 1) * 128), (unsigned*)(nxt + (wid * 4 + u) * 1024 + lane * 16), 16, 0, 0);
;         __builtin_amdgcn_global_load_lds((const unsigned*)(bp[u] + (size_t)(kt + 1) * 128), (unsigned*)(nxt + 16384 + (wid * 4 + u) * 1024 + lane * 16), 16, 0, 0);
;       }
;     }
;     FragT xa[2][4], wb[2][4];
;     asm volatile(
;         "ds_read_b128 %0, %16\n\t"
;         "ds_read_b128 %1, %16 offset:2048\n\t"
;         "ds_read_b128 %2, %16 offset:4096\n\t"
;         "ds_read_b128 %3, %16 offset:6144\n\t"
;         "ds_read_b128 %4, %18\n\t"
;         "ds_read_b128 %5, %18 offset:2048\n\t"
;         "ds_read_b128 %6, %18 offset:8192\n\t"
;         "ds_read_b128 %7, %18 offset:10240\n\t"
;         "ds_read_b128 %8, %17\n\t"
;         "ds_read_b128 %9, %17 offset:2048\n\t"
;         "ds_read_b128 %10, %17 offset:4096\n\t"
;         "ds_read_b128 %11, %17 offset:6144\n\t"
;         "ds_read_b128 %12, %19\n\t"
;         "ds_read_b128 %13, %19 offset:2048\n\t"
;         "ds_read_b128 %14, %19 offset:8192\n\t"
;         "ds_read_b128 %15, %19 offset:10240\n\t"
;         "s_waitcnt lgkmcnt(8)"
;         : "=&v"(xa[0][0]), "=&v"(xa[0][1]), "=&v"(xa[0][2]), "=&v"(xa[0][3]), "=&v"(wb[0][0]), "=&v"(wb[0][1]), "=&v"(wb[0][2]),
;           "=&v"(wb[0][3]), "=&v"(xa[1][0]), "=&v"(xa[1][1]), "=&v"(xa[1][2]), "=&v"(xa[1][3]), "=&v"(wb[1][0]), "=&v"(wb[1][1]),
;           "=&v"(wb[1][2]), "=&v"(wb[1][3])
;         : "v"(a0 + so), "v"((a0 ^ 64u) + so), "v"(b0 + so), "v"((b0 ^ 64u) + so)
;         : "memory");
;     __builtin_amdgcn_s_setprio(1);
; #pragma unroll
;     for (int i = 0; i < 4; ++i)
; #pragma unroll
;       for (int j = 0; j < 4; ++j) acc[i][j] = mma_step(wb[0][j], xa[0][i], acc[i][j]);
;     asm volatile("s_waitcnt lgkmcnt(0)"
.LBB0_734:
	s_add_i32 s37, s19, 0xffff8000
	s_and_b32 s37, s37, 0x8000
	v_add_u32_e32 v92, s37, v84
	v_add_u32_e32 v93, s37, v87
	v_or_b32_e32 v99, s37, v85
	v_or_b32_e32 v160, s37, v86
	s_and_b32 s37, s19, 0x8000
	s_add_i32 s37, s37, s62
	s_mov_b32 m0, s37
	ds_read_b128 v[88:91], v92
	global_load_lds_dwordx4 v82, s[64:65] sc1
	ds_read_b128 v[100:103], v92 offset:2048
	s_add_i32 m0, s37, 0x4000
	ds_read_b128 v[104:107], v92 offset:4096
	global_load_lds_dwordx4 v76, s[66:67] sc1
	ds_read_b128 v[108:111], v92 offset:6144
	s_add_i32 m0, s37, 0x400
	ds_read_b128 v[112:115], v99
	global_load_lds_dwordx4 v74, s[64:65] sc1
	ds_read_b128 v[116:119], v99 offset:2048
	s_add_i32 m0, s37, 0x4400
	ds_read_b128 v[120:123], v99 offset:8192
	global_load_lds_dwordx4 v72, s[66:67] sc1
	ds_read_b128 v[124:127], v99 offset:10240
	ds_read_b128 v[128:131], v93
	ds_read_b128 v[132:135], v93 offset:2048
	ds_read_b128 v[136:139], v93 offset:4096
	ds_read_b128 v[140:143], v93 offset:6144
	ds_read_b128 v[144:147], v160
	ds_read_b128 v[148:151], v160 offset:2048
	ds_read_b128 v[152:155], v160 offset:8192
	ds_read_b128 v[156:159], v160 offset:10240
	s_waitcnt lgkmcnt(8)
	s_setprio 1
	v_mfma_i32_16x16x64_i8 v[60:63], v[112:115], v[88:91], v[60:63]
	v_mfma_i32_16x16x64_i8 v[56:59], v[116:119], v[88:91], v[56:59]
	s_add_i32 m0, s37, 0x800
	v_mfma_i32_16x16x64_i8 v[52:55], v[120:123], v[88:91], v[52:55]
	global_load_lds_dwordx4 v70, s[64:65] sc1
	v_mfma_i32_16x16x64_i8 v[48:51], v[124:127], v[88:91], v[48:51]
	v_mfma_i32_16x16x64_i8 v[44:47], v[112:115], v[100:103], v[44:47]
	v_mfma_i32_16x16x64_i8 v[40:43], v[116:119], v[100:103], v[40:43]
	s_add_i32 m0, s37, 0x4800
	v_mfma_i32_16x16x64_i8 v[36:39], v[120:123], v[100:103], v[36:39]
	global_load_lds_dwordx4 v68, s[66:67] sc1
	v_mfma_i32_16x16x64_i8 v[32:35], v[124:127], v[100:103], v[32:35]
	v_mfma_i32_16x16x64_i8 v[28:31], v[112:115], v[104:107], v[28:31]
	v_mfma_i32_16x16x64_i8 v[24:27], v[116:119], v[104:107], v[24:27]
	s_add_i32 m0, s37, 0xc00
	v_mfma_i32_16x16x64_i8 v[20:23], v[120:123], v[104:107], v[20:23]
	global_load_lds_dwordx4 v66, s[64:65] sc1
	v_mfma_i32_16x16x64_i8 v[16:19], v[124:127], v[104:107], v[16:19]
	v_mfma_i32_16x16x64_i8 v[12:15], v[112:115], v[108:111], v[12:15]
	v_mfma_i32_16x16x64_i8 v[8:11], v[116:119], v[108:111], v[8:11]
	s_add_i32 m0, s37, 0x4c00
	v_mfma_i32_16x16x64_i8 v[4:7], v[120:123], v[108:111], v[4:7]
	global_load_lds_dwordx4 v64, s[66:67] sc1
	v_mfma_i32_16x16x64_i8 v[0:3], v[124:127], v[108:111], v[0:3]
	s_waitcnt lgkmcnt(0)
	s_nop 0
	v_mfma_i32_16x16x64_i8 v[60:63], v[144:147], v[128:131], v[60:63]
	v_mfma_i32_16x16x64_i8 v[56:59], v[148:151], v[128:131], v[56:59]
	v_mfma_i32_16x16x64_i8 v[52:55], v[152:155], v[128:131], v[52:55]
	v_mfma_i32_16x16x64_i8 v[48:51], v[156:159], v[128:131], v[48:51]
	v_mfma_i32_16x16x64_i8 v[44:47], v[144:147], v[132:135], v[44:47]
	v_mfma_i32_16x16x64_i8 v[40:43], v[148:151], v[132:135], v[40:43]
	v_mfma_i32_16x16x64_i8 v[36:39], v[152:155], v[132:135], v[36:39]
	v_mfma_i32_16x16x64_i8 v[32:35], v[156:159], v[132:135], v[32:35]
	v_mfma_i32_16x16x64_i8 v[28:31], v[144:147], v[136:139], v[28:31]
	v_mfma_i32_16x16x64_i8 v[24:27], v[148:151], v[136:139], v[24:27]
	v_mfma_i32_16x16x64_i8 v[20:23], v[152:155], v[136:139], v[20:23]
	v_mfma_i32_16x16x64_i8 v[16:19], v[156:159], v[136:139], v[16:19]
	v_mfma_i32_16x16x64_i8 v[12:15], v[144:147], v[140:143], v[12:15]
	v_mfma_i32_16x16x64_i8 v[8:11], v[148:151], v[140:143], v[8:11]
	v_mfma_i32_16x16x64_i8 v[4:7], v[152:155], v[140:143], v[4:7]
	v_mfma_i32_16x16x64_i8 v[0:3], v[156:159], v[140:143], v[0:3]
	s_setprio 0
	s_waitcnt vmcnt(0)
	s_add_u32 s44, s44, 0x80
	s_addc_u32 s45, s45, 0
	s_add_u32 s64, s64, 0x80
	s_addc_u32 s65, s65, 0
	s_add_u32 s66, s66, 0x80
	s_addc_u32 s67, s67, 0
	s_add_i32 s19, s19, 0x8000
	s_cmpk_lg_i32 s44, 0x780
	s_waitcnt vmcnt(0) lgkmcnt(0)
	s_barrier
	s_cbranch_scc1 .LBB0_734
	v_add_u32_e32 v76, 0x8000, v84
	v_add_u32_e32 v77, 0x8000, v87
	v_or_b32_e32 v81, 0x8000, v85
	v_or_b32_e32 v99, 0x8000, v86
	ds_read_b128 v[64:67], v76
	ds_read_b128 v[68:71], v76 offset:2048
	ds_read_b128 v[72:75], v76 offset:4096
	ds_read_b128 v[82:85], v76 offset:6144
	ds_read_b128 v[86:89], v81
	ds_read_b128 v[90:93], v81 offset:2048
	ds_read_b128 v[100:103], v81 offset:8192
	ds_read_b128 v[104:107], v81 offset:10240
	ds_read_b128 v[108:111], v77
	ds_read_b128 v[112:115], v77 offset:2048
	ds_read_b128 v[116:119], v77 offset:4096
	ds_read_b128 v[120:123], v77 offset:6144
	ds_read_b128 v[124:127], v99
	ds_read_b128 v[128:131], v99 offset:2048
	ds_read_b128 v[132:135], v99 offset:8192
	ds_read_b128 v[136:139], v99 offset:10240
	s_waitcnt lgkmcnt(8)
	s_setprio 1
	v_mfma_i32_16x16x64_i8 v[60:63], v[86:89], v[64:67], v[60:63]
	v_mfma_i32_16x16x64_i8 v[56:59], v[90:93], v[64:67], v[56:59]
	v_mfma_i32_16x16x64_i8 v[52:55], v[100:103], v[64:67], v[52:55]
	v_mfma_i32_16x16x64_i8 v[48:51], v[104:107], v[64:67], v[48:51]
	v_mfma_i32_16x16x64_i8 v[64:67], v[86:89], v[68:71], v[44:47]
	v_mfma_i32_16x16x64_i8 v[40:43], v[90:93], v[68:71], v[40:43]
	v_mfma_i32_16x16x64_i8 v[36:39], v[100:103], v[68:71], v[36:39]
	v_mfma_i32_16x16x64_i8 v[32:35], v[104:107], v[68:71], v[32:35]
	v_mfma_i32_16x16x64_i8 v[68:71], v[86:89], v[72:75], v[28:31]
	v_mfma_i32_16x16x64_i8 v[24:27], v[90:93], v[72:75], v[24:27]
	v_mfma_i32_16x16x64_i8 v[20:23], v[100:103], v[72:75], v[20:23]
	v_mfma_i32_16x16x64_i8 v[16:19], v[104:107], v[72:75], v[16:19]
	v_mfma_i32_16x16x64_i8 v[74:77], v[86:89], v[82:85], v[12:15]
	v_mfma_i32_16x16x64_i8 v[8:11], v[90:93], v[82:85], v[8:11]
	v_mfma_i32_16x16x64_i8 v[86:89], v[100:103], v[82:85], v[4:7]
	v_mfma_i32_16x16x64_i8 v[82:85], v[104:107], v[82:85], v[0:3]
	s_waitcnt lgkmcnt(0)
	s_nop 0
	v_mfma_i32_16x16x64_i8 v[56:59], v[128:131], v[108:111], v[56:59]
	v_mfma_i32_16x16x64_i8 v[140:143], v[132:135], v[108:111], v[52:55]
	v_mfma_i32_16x16x64_i8 v[46:49], v[136:139], v[108:111], v[48:51]
	v_mfma_i32_16x16x64_i8 v[52:55], v[124:127], v[112:115], v[64:67]
	v_mfma_i32_16x16x64_i8 v[40:43], v[128:131], v[112:115], v[40:43]
	v_mfma_i32_16x16x64_i8 v[36:39], v[132:135], v[112:115], v[36:39]
	v_mfma_i32_16x16x64_i8 v[30:33], v[136:139], v[112:115], v[32:35]
	v_mfma_i32_16x16x64_i8 v[24:27], v[128:131], v[116:119], v[24:27]
	v_mfma_i32_16x16x64_i8 v[20:23], v[132:135], v[116:119], v[20:23]
	v_mfma_i32_16x16x64_i8 v[14:17], v[136:139], v[116:119], v[16:19]
	v_mfma_i32_16x16x64_i8 v[4:7], v[124:127], v[120:123], v[74:77]
	v_mfma_i32_16x16x64_i8 v[0:3], v[128:131], v[120:123], v[8:11]
	v_mfma_i32_16x16x64_i8 v[8:11], v[136:139], v[120:123], v[82:85]
	v_mfma_i32_16x16x64_i8 v[102:105], v[124:127], v[108:111], v[60:63]
	v_mfma_i32_16x16x64_i8 v[70:73], v[124:127], v[116:119], v[68:71]
	v_mfma_i32_16x16x64_i8 v[62:65], v[132:135], v[120:123], v[86:89]
	s_setprio 0
	s_waitcnt vmcnt(0)
	s_barrier
; #define P (*launderP(lp))
; DEV int rowmap(int p, int Sshift, int dl) {
;   int seq = p >> Sshift, pp = p & ((1 << Sshift) - 1);
;   int Lshift = Sshift - dl;
;   int r = pp >> Lshift, l = pp & ((1 << Lshift) - 1);
;   return (seq << Sshift) + (l << dl) + r;
; }
; __device__ __forceinline__ void phase_gemm1(PREF P, int slab, char* smem) {
;     ...
; #pragma unroll
;       for (int i = 0; i < 4; ++i) {
;         const float sxr = P.sx[rowmap(m0 + wm * 64 + i * 16 + l15, Sshift, dl)];
; #pragma unroll
;         for (int j = 0; j < 4; ++j) {
;           const float4 swc = *(const float4*)(P.sw + n0 + (j & 1) * 16 + wn * 32 + (j >> 1) * 64 + q * 4);
;           acc[i][j][0] = (float)iacc[i][j][0] * sxr * swc.x; acc[i][j][1] = (float)iacc[i][j][1] * sxr * swc.y;
;           acc[i][j][2] = (float)iacc[i][j][2] * sxr * swc.z; acc[i][j][3] = (float)iacc[i][j][3] * sxr * swc.w;
;         }
;       }
	s_nop 0
	ds_read2_b64 v[84:87], v79 offset0:52 offset1:53
	v_add_u32_e32 v28, s36, v94
	v_mov_b32_e32 v29, s51
	v_and_b32_e32 v101, s51, v28
	v_bitop3_b32 v19, v28, s18, v29 bitop3:0x80
	v_lshrrev_b32_e32 v18, s17, v101
	v_and_b32_e32 v34, s50, v28
	v_lshlrev_b32_e32 v19, s6, v19
	v_add3_u32 v18, v18, v34, v19
	v_ashrrev_i32_e32 v19, 31, v18
	s_waitcnt lgkmcnt(0)
	v_lshl_add_u64 v[18:19], v[18:19], 2, v[84:85]
	flat_load_dword v82, v[18:19]
	v_or_b32_e32 v18, 16, v28
	v_bitop3_b32 v100, v28, s51, 16 bitop3:0xc8
	v_bitop3_b32 v18, v18, s18, v29 bitop3:0x80
	s_ashr_i32 s41, s40, 31
	v_lshrrev_b32_e32 v19, s17, v100
	v_lshlrev_b32_e32 v18, s6, v18
	v_lshl_add_u64 v[12:13], s[40:41], 2, v[86:87]
	v_mov_b32_e32 v81, v181
	v_add3_u32 v18, v19, v34, v18
	v_lshl_add_u64 v[12:13], v[12:13], 0, v[80:81]
	v_ashrrev_i32_e32 v19, 31, v18
	v_lshlrev_b32_e32 v180, 2, v78
	v_lshl_add_u64 v[18:19], v[18:19], 2, v[84:85]
	v_lshl_add_u64 v[12:13], v[12:13], 0, v[180:181]
	flat_load_dword v114, v[18:19]
	flat_load_dwordx4 v[106:109], v[12:13]
	flat_load_dwordx4 v[110:113], v[12:13] offset:256
	flat_load_dwordx4 v[74:77], v[12:13] offset:64
	flat_load_dwordx4 v[66:69], v[12:13] offset:320
	v_or_b32_e32 v12, 32, v28
	v_bitop3_b32 v99, v28, s51, 32 bitop3:0xc8
	v_bitop3_b32 v12, v12, s18, v29 bitop3:0x80
	v_lshrrev_b32_e32 v13, s17, v99
	v_lshlrev_b32_e32 v12, s6, v12
	v_add3_u32 v12, v13, v34, v12
	v_ashrrev_i32_e32 v13, 31, v12
	v_lshl_add_u64 v[12:13], v[12:13], 2, v[84:85]
	flat_load_dword v116, v[12:13]
	v_or_b32_e32 v12, 48, v28
	v_bitop3_b32 v81, v28, s51, 48 bitop3:0xc8
	v_bitop3_b32 v12, v12, s18, v29 bitop3:0x80
	v_lshrrev_b32_e32 v18, s17, v81
	v_lshlrev_b32_e32 v12, s6, v12
	v_add3_u32 v18, v18, v34, v12
	v_ashrrev_i32_e32 v19, 31, v18
	v_lshl_add_u64 v[18:19], v[18:19], 2, v[84:85]
	flat_load_dword v118, v[18:19]
	v_cvt_f32_i32_e32 v19, v143
	v_cvt_f32_i32_e32 v18, v105
	v_cvt_f32_i32_e32 v29, v48
	v_cvt_f32_i32_e32 v28, v58
	v_cvt_f32_i32_e32 v13, v142
	v_cvt_f32_i32_e32 v12, v104
	v_cvt_f32_i32_e32 v35, v49
	v_cvt_f32_i32_e32 v34, v59
	v_cvt_f32_i32_e32 v49, v32
	v_cvt_f32_i32_e32 v33, v33
	v_cvt_f32_i32_e32 v32, v43
	v_cvt_f32_i32_e32 v59, v22
	v_cvt_f32_i32_e32 v58, v72
	v_cvt_f32_i32_e32 v45, v38
	v_cvt_f32_i32_e32 v44, v54
	v_cvt_f32_i32_e32 v38, v55
	v_cvt_f32_i32_e32 v48, v42
	v_cvt_f32_i32_e32 v5, v5
	v_cvt_f32_i32_e32 v4, v4
	v_cvt_f32_i32_e32 v25, v25
	v_cvt_f32_i32_e32 v24, v24
	v_cvt_f32_i32_e32 v15, v15
	v_cvt_f32_i32_e32 v14, v14
	v_cvt_f32_i32_e32 v31, v31
	v_cvt_f32_i32_e32 v30, v30
	v_cvt_f32_i32_e32 v1, v1
	v_cvt_f32_i32_e32 v0, v0
	v_cvt_f32_i32_e32 v39, v39
	v_cvt_f32_i32_e32 v11, v11
	s_andn2_b64 vcc, exec, s[14:15]
	s_waitcnt vmcnt(0) lgkmcnt(0)
	v_pk_mul_f32 v[18:19], v[82:83], v[18:19] op_sel_hi:[0,1]
	v_pk_mul_f32 v[28:29], v[82:83], v[28:29] op_sel_hi:[0,1]
	v_pk_mul_f32 v[12:13], v[82:83], v[12:13] op_sel_hi:[0,1]
	v_pk_mul_f32 v[34:35], v[82:83], v[34:35] op_sel_hi:[0,1]
	v_mov_b32_e32 v84, v108
	v_mov_b32_e32 v85, v112
	v_mov_b32_e32 v112, v109
	v_mov_b32_e32 v104, v76
	v_mov_b32_e32 v105, v68
	v_pk_mul_f32 v[54:55], v[18:19], v[112:113]
	v_cvt_f32_i32_e32 v19, v23
	v_cvt_f32_i32_e32 v18, v73
	v_pk_mul_f32 v[42:43], v[28:29], v[104:105]
	v_cvt_f32_i32_e32 v29, v16
	v_cvt_f32_i32_e32 v28, v26
	v_mov_b32_e32 v68, v77
	v_pk_mul_f32 v[88:89], v[12:13], v[84:85]
	v_pk_mul_f32 v[12:13], v[114:115], v[32:33] op_sel_hi:[0,1]
	v_pk_mul_f32 v[50:51], v[34:35], v[68:69]
	v_pk_mul_f32 v[34:35], v[68:69], v[12:13]
	v_pk_mul_f32 v[12:13], v[116:117], v[58:59] op_sel_hi:[0,1]
	v_pk_mul_f32 v[86:87], v[84:85], v[12:13]
	v_pk_mul_f32 v[12:13], v[116:117], v[18:19] op_sel_hi:[0,1]
	v_pk_mul_f32 v[22:23], v[112:113], v[12:13]
	v_pk_mul_f32 v[12:13], v[116:117], v[28:29] op_sel_hi:[0,1]
	v_pk_mul_f32 v[76:77], v[104:105], v[12:13]
	v_cvt_f32_i32_e32 v13, v17
	v_cvt_f32_i32_e32 v12, v27
	v_cvt_f32_i32_e32 v17, v103
	v_cvt_f32_i32_e32 v16, v102
	v_cvt_f32_i32_e32 v27, v141
	v_cvt_f32_i32_e32 v26, v140
	v_cvt_f32_i32_e32 v29, v37
	v_cvt_f32_i32_e32 v28, v36
	v_pk_mul_f32 v[12:13], v[116:117], v[12:13] op_sel_hi:[0,1]
	v_pk_mul_f32 v[18:19], v[68:69], v[12:13]
	v_pk_mul_f32 v[12:13], v[82:83], v[16:17] op_sel_hi:[0,1]
	v_pk_mul_f32 v[16:17], v[82:83], v[26:27] op_sel_hi:[0,1]
	v_cvt_f32_i32_e32 v27, v53
	v_cvt_f32_i32_e32 v26, v52
	v_pk_mul_f32 v[52:53], v[16:17], v[110:111]
	v_pk_mul_f32 v[16:17], v[114:115], v[28:29] op_sel_hi:[0,1]
	v_pk_mul_f32 v[36:37], v[110:111], v[16:17]
	v_cvt_f32_i32_e32 v17, v21
	v_cvt_f32_i32_e32 v16, v20
	v_pk_mul_f32 v[44:45], v[114:115], v[44:45] op_sel_hi:[0,1]
	v_pk_mul_f32 v[60:61], v[106:107], v[12:13]
	v_pk_mul_f32 v[12:13], v[114:115], v[26:27] op_sel_hi:[0,1]
	v_pk_mul_f32 v[92:93], v[84:85], v[44:45]
	v_pk_mul_f32 v[44:45], v[106:107], v[12:13]
	v_cvt_f32_i32_e32 v13, v71
	v_cvt_f32_i32_e32 v12, v70
	v_pk_mul_f32 v[16:17], v[116:117], v[16:17] op_sel_hi:[0,1]
	v_pk_mul_f32 v[20:21], v[110:111], v[16:17]
	v_cvt_f32_i32_e32 v17, v63
	v_cvt_f32_i32_e32 v16, v62
	v_cvt_f32_i32_e32 v27, v64
	v_cvt_f32_i32_e32 v26, v6
	v_pk_mul_f32 v[12:13], v[116:117], v[12:13] op_sel_hi:[0,1]
	v_pk_mul_f32 v[4:5], v[118:119], v[4:5] op_sel_hi:[0,1]
	v_pk_mul_f32 v[28:29], v[106:107], v[12:13]
	v_pk_mul_f32 v[12:13], v[106:107], v[4:5]
	v_pk_mul_f32 v[4:5], v[118:119], v[16:17] op_sel_hi:[0,1]
	v_pk_mul_f32 v[16:17], v[118:119], v[26:27] op_sel_hi:[0,1]
	v_pk_mul_f32 v[84:85], v[84:85], v[16:17]
	v_cvt_f32_i32_e32 v17, v65
	v_cvt_f32_i32_e32 v16, v7
	v_cvt_f32_i32_e32 v27, v57
	v_cvt_f32_i32_e32 v26, v56
	v_cvt_f32_i32_e32 v33, v47
	v_cvt_f32_i32_e32 v32, v46
	v_pk_mul_f32 v[6:7], v[118:119], v[16:17] op_sel_hi:[0,1]
; #define P (*launderP(lp))
; __device__ __forceinline__ void phase_gemm1(PREF P, int slab, char* smem) {
;     ...
;       for (int i = 0; i < 4; ++i) {
;         const float sxr = P.sx[rowmap(m0 + wm * 64 + i * 16 + l15, Sshift, dl)];
; #pragma unroll
;         for (int j = 0; j < 4; ++j) {
;           const float4 swc = *(const float4*)(P.sw + n0 + (j & 1) * 16 + wn * 32 + (j >> 1) * 64 + q * 4);
;           acc[i][j][0] = (float)iacc[i][j][0] * sxr * swc.x; acc[i][j][1] = (float)iacc[i][j][1] * sxr * swc.y;
;           acc[i][j][2] = (float)iacc[i][j][2] * sxr * swc.z; acc[i][j][3] = (float)iacc[i][j][3] * sxr * swc.w;
;         }
;       }
;     }
;     if (region <= 1) {
; #pragma unroll
;       for (int i = 0; i < 4; ++i) {
;         const int row = m0 + wm * 64 + i * 16 + l15;
;         const float s = (float)(row & ((1 << Sshift) - 1));
; #pragma unroll
;         for (int jj = 0; jj < 2; ++jj)
; #pragma unroll
;           for (int r = 0; r < 4; ++r) {
;             const int d = jj * 16 + wn * 32 + q * 4 + r;
;             float fr = __builtin_amdgcn_fractf(s * P.ropec[d]);
;             float cs = __builtin_amdgcn_cosf(fr), sn = __builtin_amdgcn_sinf(fr);
;             float t1 = acc[i][jj][r], t2 = acc[i][jj + 2][r];
;             float o1 = t1 * cs - t2 * sn, o2 = t1 * sn + t2 * cs;
;             if (region == 1) { o1 *= QK_SCALE; o2 *= QK_SCALE; }
;             acc[i][jj][r] = o1;
;             acc[i][jj + 2][r] = o2;
;           }
	v_pk_mul_f32 v[16:17], v[82:83], v[26:27] op_sel_hi:[0,1]
	v_pk_mul_f32 v[56:57], v[16:17], v[74:75]
	v_pk_mul_f32 v[26:27], v[82:83], v[32:33] op_sel_hi:[0,1]
	v_cvt_f32_i32_e32 v33, v41
	v_cvt_f32_i32_e32 v32, v40
	v_pk_mul_f32 v[48:49], v[114:115], v[48:49] op_sel_hi:[0,1]
	v_pk_mul_f32 v[14:15], v[116:117], v[14:15] op_sel_hi:[0,1]
	v_pk_mul_f32 v[90:91], v[104:105], v[48:49]
	v_pk_mul_f32 v[16:17], v[114:115], v[32:33] op_sel_hi:[0,1]
	v_pk_mul_f32 v[40:41], v[74:75], v[16:17]
	v_pk_mul_f32 v[16:17], v[116:117], v[24:25] op_sel_hi:[0,1]
	v_pk_mul_f32 v[48:49], v[26:27], v[66:67]
	v_pk_mul_f32 v[26:27], v[114:115], v[30:31] op_sel_hi:[0,1]
	v_pk_mul_f32 v[24:25], v[74:75], v[16:17]
	v_pk_mul_f32 v[16:17], v[66:67], v[14:15]
	v_cvt_f32_i32_e32 v15, v10
	v_cvt_f32_i32_e32 v14, v2
	v_pk_mul_f32 v[32:33], v[66:67], v[26:27]
	v_cvt_f32_i32_e32 v27, v9
	v_cvt_f32_i32_e32 v26, v8
	v_cvt_f32_i32_e32 v10, v3
	v_pk_mul_f32 v[0:1], v[118:119], v[0:1] op_sel_hi:[0,1]
	v_pk_mul_f32 v[2:3], v[118:119], v[14:15] op_sel_hi:[0,1]
	v_pk_mul_f32 v[38:39], v[114:115], v[38:39] op_sel_hi:[0,1]
	v_pk_mul_f32 v[8:9], v[74:75], v[0:1]
	v_pk_mul_f32 v[0:1], v[118:119], v[26:27] op_sel_hi:[0,1]
	v_pk_mul_f32 v[82:83], v[104:105], v[2:3]
	v_pk_mul_f32 v[2:3], v[118:119], v[10:11] op_sel_hi:[0,1]
	v_pk_mul_f32 v[38:39], v[112:113], v[38:39]
	v_pk_mul_f32 v[4:5], v[110:111], v[4:5]
	v_pk_mul_f32 v[6:7], v[112:113], v[6:7]
	v_pk_mul_f32 v[0:1], v[66:67], v[0:1]
	v_pk_mul_f32 v[2:3], v[68:69], v[2:3]
	s_cbranch_vccnz .LBB0_737
	ds_read2_b32 v[10:11], v96 offset0:134 offset1:135
	v_cvt_f32_u32_e32 v26, v101
	v_mov_b32_e32 v30, v60
	v_mov_b32_e32 v31, v52
	v_mov_b32_e32 v46, v61
	s_waitcnt lgkmcnt(0)
	v_mul_f32_e32 v14, v10, v26
	v_fract_f32_e32 v15, v14
	v_cos_f32_e32 v14, v15
	v_sin_f32_e32 v15, v15
	v_mov_b32_e32 v47, v53
	v_pk_mul_f32 v[30:31], v[30:31], v[14:15]
	s_nop 0
	v_sub_f32_e32 v27, v30, v31
	v_mul_f32_e32 v30, 0x3db504f3, v27
	v_cndmask_b32_e64 v62, v27, v30, s[42:43]
	v_mul_f32_e32 v27, v11, v26
	v_fract_f32_e32 v27, v27
	v_cos_f32_e32 v30, v27
	v_sin_f32_e32 v31, v27
	s_nop 0
	v_pk_mul_f32 v[46:47], v[46:47], v[30:31]
	s_nop 0
	v_sub_f32_e32 v27, v46, v47
	v_mov_b32_e32 v46, v15
	v_mov_b32_e32 v15, v30
	v_mov_b32_e32 v47, v31
	v_pk_mul_f32 v[14:15], v[52:53], v[14:15]
	v_mul_f32_e32 v63, 0x3db504f3, v27
	v_pk_fma_f32 v[14:15], v[60:61], v[46:47], v[14:15]
	v_cndmask_b32_e64 v63, v27, v63, s[42:43]
	v_pk_mul_f32 v[30:31], v[14:15], s[12:13] op_sel_hi:[1,0]
	v_mov_b32_e32 v52, v57
	v_cndmask_b32_e64 v59, v15, v31, s[42:43]
	v_cndmask_b32_e64 v58, v14, v30, s[42:43]
	ds_read2_b32 v[14:15], v96 offset0:136 offset1:137
	v_mov_b32_e32 v53, v49
	s_waitcnt lgkmcnt(0)
	v_mul_f32_e32 v27, v14, v26
	v_fract_f32_e32 v27, v27
	v_cos_f32_e32 v30, v27
	v_sin_f32_e32 v31, v27
	s_nop 0
	v_pk_mul_f32 v[46:47], v[88:89], v[30:31]
	s_nop 0
	v_sub_f32_e32 v27, v46, v47
	v_mov_b32_e32 v46, v31
	v_mov_b32_e32 v47, v30
	v_pk_mul_f32 v[30:31], v[88:89], v[46:47]
	ds_read2_b32 v[88:89], v96 offset0:150 offset1:151
	v_add_f32_e32 v30, v30, v31
	v_mul_f32_e32 v31, 0x3db504f3, v27
	v_cndmask_b32_e64 v64, v27, v31, s[42:43]
	v_mul_f32_e32 v27, v15, v26
	v_mul_f32_e32 v46, 0x3db504f3, v30
	v_fract_f32_e32 v27, v27
	v_cndmask_b32_e64 v60, v30, v46, s[42:43]
	v_cos_f32_e32 v30, v27
	v_sin_f32_e32 v31, v27
	s_nop 0
	v_pk_mul_f32 v[46:47], v[54:55], v[30:31]
	s_nop 0
	v_sub_f32_e32 v27, v46, v47
	v_mov_b32_e32 v46, v31
	v_mov_b32_e32 v47, v30
	v_pk_mul_f32 v[30:31], v[54:55], v[46:47]
	v_mov_b32_e32 v47, v48
	v_add_f32_e32 v30, v30, v31
	v_mul_f32_e32 v31, 0x3db504f3, v27
	v_cndmask_b32_e64 v65, v27, v31, s[42:43]
	s_waitcnt lgkmcnt(0)
	v_mul_f32_e32 v27, v88, v26
	v_mul_f32_e32 v46, 0x3db504f3, v30
	v_fract_f32_e32 v27, v27
	v_cndmask_b32_e64 v61, v30, v46, s[42:43]
	v_cos_f32_e32 v30, v27
	v_sin_f32_e32 v31, v27
	v_mov_b32_e32 v46, v56
	v_pk_mul_f32 v[46:47], v[46:47], v[30:31]
	s_nop 0
	v_sub_f32_e32 v27, v46, v47
	v_mul_f32_e32 v46, 0x3db504f3, v27
	v_cndmask_b32_e64 v66, v27, v46, s[42:43]
	v_mul_f32_e32 v27, v89, v26
	v_fract_f32_e32 v27, v27
	v_cos_f32_e32 v46, v27
	v_sin_f32_e32 v47, v27
	s_nop 0
	v_pk_mul_f32 v[52:53], v[52:53], v[46:47]
	s_nop 0
	v_sub_f32_e32 v27, v52, v53
	v_mov_b32_e32 v52, v31
	v_mov_b32_e32 v31, v46
	v_mov_b32_e32 v53, v47
	v_pk_mul_f32 v[30:31], v[48:49], v[30:31]
	v_mul_f32_e32 v54, 0x3db504f3, v27
	v_pk_fma_f32 v[30:31], v[56:57], v[52:53], v[30:31]
	ds_read2_b32 v[56:57], v96 offset0:152 offset1:153
	v_cndmask_b32_e64 v67, v27, v54, s[42:43]
	v_pk_mul_f32 v[46:47], v[30:31], s[12:13] op_sel_hi:[1,0]
	s_waitcnt lgkmcnt(0)
; #define P (*launderP(lp))
; __device__ __forceinline__ void phase_gemm1(PREF P, int slab, char* smem) {
;     ...
;       for (int i = 0; i < 4; ++i) {
;         const int row = m0 + wm * 64 + i * 16 + l15;
;         const float s = (float)(row & ((1 << Sshift) - 1));
; #pragma unroll
;         for (int jj = 0; jj < 2; ++jj)
; #pragma unroll
;           for (int r = 0; r < 4; ++r) {
;             const int d = jj * 16 + wn * 32 + q * 4 + r;
;             float fr = __builtin_amdgcn_fractf(s * P.ropec[d]);
;             float cs = __builtin_amdgcn_cosf(fr), sn = __builtin_amdgcn_sinf(fr);
;             float t1 = acc[i][jj][r], t2 = acc[i][jj + 2][r];
;             float o1 = t1 * cs - t2 * sn, o2 = t1 * sn + t2 * cs;
;             if (region == 1) { o1 *= QK_SCALE; o2 *= QK_SCALE; }
;             acc[i][jj][r] = o1;
;             acc[i][jj + 2][r] = o2;
;           }
	v_mul_f32_e32 v27, v56, v26
	v_fract_f32_e32 v27, v27
	v_cndmask_b32_e64 v53, v31, v47, s[42:43]
	v_cndmask_b32_e64 v52, v30, v46, s[42:43]
	v_cos_f32_e32 v30, v27
	v_sin_f32_e32 v31, v27
	v_mul_f32_e32 v26, v57, v26
	v_pk_mul_f32 v[46:47], v[42:43], v[30:31]
	s_nop 0
	v_sub_f32_e32 v27, v46, v47
	v_mov_b32_e32 v46, v31
	v_mov_b32_e32 v47, v30
	v_pk_mul_f32 v[30:31], v[42:43], v[46:47]
	v_mov_b32_e32 v43, v37
	v_add_f32_e32 v30, v30, v31
	v_mul_f32_e32 v31, 0x3db504f3, v27
	v_cndmask_b32_e64 v68, v27, v31, s[42:43]
	v_fract_f32_e32 v27, v26
	v_cos_f32_e32 v26, v27
	v_sin_f32_e32 v27, v27
	v_mul_f32_e32 v42, 0x3db504f3, v30
	v_cndmask_b32_e64 v54, v30, v42, s[42:43]
	v_pk_mul_f32 v[30:31], v[50:51], v[26:27]
	s_nop 0
	v_sub_f32_e32 v42, v30, v31
	v_mov_b32_e32 v30, v27
	v_mov_b32_e32 v31, v26
	v_pk_mul_f32 v[26:27], v[50:51], v[30:31]
	v_cvt_f32_u32_e32 v50, v100
	v_add_f32_e32 v26, v26, v27
	v_mul_f32_e32 v30, 0x3db504f3, v26
	v_mul_f32_e32 v27, 0x3db504f3, v42
	v_cndmask_b32_e64 v55, v26, v30, s[42:43]
	v_mul_f32_e32 v26, v10, v50
	v_cndmask_b32_e64 v69, v42, v27, s[42:43]
	v_fract_f32_e32 v27, v26
	v_cos_f32_e32 v26, v27
	v_sin_f32_e32 v27, v27
	v_mov_b32_e32 v30, v44
	v_mov_b32_e32 v31, v36
	v_mov_b32_e32 v42, v45
	v_pk_mul_f32 v[30:31], v[30:31], v[26:27]
	s_nop 0
	v_sub_f32_e32 v30, v30, v31
	v_mul_f32_e32 v31, 0x3db504f3, v30
	v_cndmask_b32_e64 v46, v30, v31, s[42:43]
	v_mul_f32_e32 v30, v11, v50
	v_fract_f32_e32 v31, v30
	v_cos_f32_e32 v30, v31
	v_sin_f32_e32 v31, v31
	s_nop 0
	v_pk_mul_f32 v[42:43], v[42:43], v[30:31]
	s_nop 0
	v_sub_f32_e32 v47, v42, v43
	v_mov_b32_e32 v42, v27
	v_mov_b32_e32 v27, v30
	v_mov_b32_e32 v43, v31
	v_pk_mul_f32 v[26:27], v[36:37], v[26:27]
	v_mul_f32_e32 v48, 0x3db504f3, v47
	v_pk_fma_f32 v[26:27], v[44:45], v[42:43], v[26:27]
	v_cndmask_b32_e64 v47, v47, v48, s[42:43]
	v_pk_mul_f32 v[30:31], v[26:27], s[12:13] op_sel_hi:[1,0]
	v_mov_b32_e32 v37, v33
	v_cndmask_b32_e64 v42, v26, v30, s[42:43]
	v_mul_f32_e32 v26, v14, v50
	v_cndmask_b32_e64 v43, v27, v31, s[42:43]
	v_fract_f32_e32 v27, v26
	v_cos_f32_e32 v26, v27
	v_sin_f32_e32 v27, v27
	s_nop 0
	v_pk_mul_f32 v[30:31], v[92:93], v[26:27]
	s_nop 0
	v_sub_f32_e32 v36, v30, v31
	v_mov_b32_e32 v30, v27
	v_mov_b32_e32 v31, v26
	v_pk_mul_f32 v[26:27], v[92:93], v[30:31]
	s_nop 0
	v_add_f32_e32 v26, v26, v27
	v_mul_f32_e32 v30, 0x3db504f3, v26
	v_mul_f32_e32 v27, 0x3db504f3, v36
	v_cndmask_b32_e64 v44, v26, v30, s[42:43]
	v_mul_f32_e32 v26, v15, v50
	v_cndmask_b32_e64 v48, v36, v27, s[42:43]
	v_fract_f32_e32 v27, v26
	v_cos_f32_e32 v26, v27
	v_sin_f32_e32 v27, v27
	s_nop 0
	v_pk_mul_f32 v[30:31], v[38:39], v[26:27]
	s_nop 0
	v_sub_f32_e32 v36, v30, v31
	v_mov_b32_e32 v30, v27
	v_mov_b32_e32 v31, v26
	v_pk_mul_f32 v[26:27], v[38:39], v[30:31]
	v_mov_b32_e32 v31, v32
	v_add_f32_e32 v26, v26, v27
	v_mul_f32_e32 v30, 0x3db504f3, v26
	v_mul_f32_e32 v27, 0x3db504f3, v36
	v_cndmask_b32_e64 v45, v26, v30, s[42:43]
	v_mul_f32_e32 v26, v88, v50
	v_cndmask_b32_e64 v49, v36, v27, s[42:43]
	v_fract_f32_e32 v27, v26
	v_cos_f32_e32 v26, v27
	v_sin_f32_e32 v27, v27
	v_mov_b32_e32 v30, v40
	v_mov_b32_e32 v36, v41
	v_pk_mul_f32 v[30:31], v[30:31], v[26:27]
	s_nop 0
	v_sub_f32_e32 v30, v30, v31
	v_mul_f32_e32 v31, 0x3db504f3, v30
	v_cndmask_b32_e64 v70, v30, v31, s[42:43]
	v_mul_f32_e32 v30, v89, v50
	v_fract_f32_e32 v31, v30
	v_cos_f32_e32 v30, v31
	v_sin_f32_e32 v31, v31
	s_nop 0
	v_pk_mul_f32 v[36:37], v[36:37], v[30:31]
	s_nop 0
	v_sub_f32_e32 v38, v36, v37
	v_mov_b32_e32 v36, v27
	v_mov_b32_e32 v27, v30
	v_mov_b32_e32 v37, v31
	v_pk_mul_f32 v[26:27], v[32:33], v[26:27]
	v_mul_f32_e32 v39, 0x3db504f3, v38
	v_pk_fma_f32 v[26:27], v[40:41], v[36:37], v[26:27]
	v_cndmask_b32_e64 v71, v38, v39, s[42:43]
	v_pk_mul_f32 v[30:31], v[26:27], s[12:13] op_sel_hi:[1,0]
	v_cvt_f32_u32_e32 v40, v99
	v_cndmask_b32_e64 v36, v26, v30, s[42:43]
	v_mul_f32_e32 v26, v56, v50
	v_cndmask_b32_e64 v37, v27, v31, s[42:43]
	v_fract_f32_e32 v27, v26
	v_cos_f32_e32 v26, v27
	v_sin_f32_e32 v27, v27
	s_nop 0
	v_pk_mul_f32 v[30:31], v[90:91], v[26:27]
	s_nop 0
	v_sub_f32_e32 v32, v30, v31
	v_mov_b32_e32 v30, v27
	v_mov_b32_e32 v31, v26
	v_pk_mul_f32 v[26:27], v[90:91], v[30:31]
	s_nop 0
	v_add_f32_e32 v26, v26, v27
	v_mul_f32_e32 v30, 0x3db504f3, v26
	v_mul_f32_e32 v27, 0x3db504f3, v32
	v_cndmask_b32_e64 v38, v26, v30, s[42:43]
	v_mul_f32_e32 v26, v57, v50
	v_cndmask_b32_e64 v72, v32, v27, s[42:43]
	v_fract_f32_e32 v27, v26
	v_cos_f32_e32 v26, v27
	v_sin_f32_e32 v27, v27
	s_nop 0
	v_pk_mul_f32 v[30:31], v[34:35], v[26:27]
	s_nop 0
	v_sub_f32_e32 v32, v30, v31
	v_mov_b32_e32 v30, v27
	v_mov_b32_e32 v31, v26
	v_pk_mul_f32 v[26:27], v[34:35], v[30:31]
	v_mov_b32_e32 v31, v20
	v_add_f32_e32 v26, v26, v27
	v_mul_f32_e32 v30, 0x3db504f3, v26
	v_mul_f32_e32 v27, 0x3db504f3, v32
	v_cndmask_b32_e64 v39, v26, v30, s[42:43]
	v_mul_f32_e32 v26, v10, v40
	v_cndmask_b32_e64 v73, v32, v27, s[42:43]
	v_fract_f32_e32 v27, v26
	v_cos_f32_e32 v26, v27
	v_sin_f32_e32 v27, v27
	v_mov_b32_e32 v30, v28
	v_mov_b32_e32 v34, v29
	v_mov_b32_e32 v35, v21
	v_pk_mul_f32 v[30:31], v[30:31], v[26:27]
	s_nop 0
	v_sub_f32_e32 v30, v30, v31
	v_mul_f32_e32 v31, 0x3db504f3, v30
	v_cndmask_b32_e64 v30, v30, v31, s[42:43]
	v_mul_f32_e32 v31, v11, v40
	v_fract_f32_e32 v31, v31
	v_cos_f32_e32 v32, v31
	v_sin_f32_e32 v33, v31
	s_nop 0
	v_pk_mul_f32 v[34:35], v[34:35], v[32:33]
	s_nop 0
	v_sub_f32_e32 v31, v34, v35
	v_mov_b32_e32 v34, v27
	v_mov_b32_e32 v27, v32
	v_mov_b32_e32 v35, v33
	v_pk_mul_f32 v[20:21], v[20:21], v[26:27]
	v_mul_f32_e32 v41, 0x3db504f3, v31
	v_pk_fma_f32 v[20:21], v[28:29], v[34:35], v[20:21]
	v_cndmask_b32_e64 v31, v31, v41, s[42:43]
; #define P (*launderP(lp))
; __device__ __forceinline__ void phase_gemm1(PREF P, int slab, char* smem) {
;     ...
;       for (int i = 0; i < 4; ++i) {
;         const int row = m0 + wm * 64 + i * 16 + l15;
;         const float s = (float)(row & ((1 << Sshift) - 1));
; #pragma unroll
;         for (int jj = 0; jj < 2; ++jj)
; #pragma unroll
;           for (int r = 0; r < 4; ++r) {
;             const int d = jj * 16 + wn * 32 + q * 4 + r;
;             float fr = __builtin_amdgcn_fractf(s * P.ropec[d]);
;             float cs = __builtin_amdgcn_cosf(fr), sn = __builtin_amdgcn_sinf(fr);
;             float t1 = acc[i][jj][r], t2 = acc[i][jj + 2][r];
;             float o1 = t1 * cs - t2 * sn, o2 = t1 * sn + t2 * cs;
;             if (region == 1) { o1 *= QK_SCALE; o2 *= QK_SCALE; }
;             acc[i][jj][r] = o1;
;             acc[i][jj + 2][r] = o2;
;           }
	v_pk_mul_f32 v[26:27], v[20:21], s[12:13] op_sel_hi:[1,0]
	s_nop 0
	v_cndmask_b32_e64 v26, v20, v26, s[42:43]
	v_mul_f32_e32 v20, v14, v40
	v_cndmask_b32_e64 v27, v21, v27, s[42:43]
	v_fract_f32_e32 v21, v20
	v_cos_f32_e32 v20, v21
	v_sin_f32_e32 v21, v21
	s_nop 0
	v_pk_mul_f32 v[28:29], v[86:87], v[20:21]
	s_nop 0
	v_sub_f32_e32 v32, v28, v29
	v_mov_b32_e32 v28, v21
	v_mov_b32_e32 v29, v20
	v_pk_mul_f32 v[20:21], v[86:87], v[28:29]
	s_nop 0
	v_add_f32_e32 v20, v20, v21
	v_mul_f32_e32 v28, 0x3db504f3, v20
	v_mul_f32_e32 v21, 0x3db504f3, v32
	v_cndmask_b32_e64 v28, v20, v28, s[42:43]
	v_mul_f32_e32 v20, v15, v40
	v_cndmask_b32_e64 v32, v32, v21, s[42:43]
	v_fract_f32_e32 v21, v20
	v_cos_f32_e32 v20, v21
	v_sin_f32_e32 v21, v21
	s_nop 0
	v_pk_mul_f32 v[34:35], v[22:23], v[20:21]
	s_nop 0
	v_sub_f32_e32 v33, v34, v35
	v_mov_b32_e32 v34, v21
	v_mov_b32_e32 v35, v20
	v_pk_mul_f32 v[20:21], v[22:23], v[34:35]
	v_mov_b32_e32 v23, v16
	v_add_f32_e32 v20, v20, v21
	v_mul_f32_e32 v22, 0x3db504f3, v20
	v_mul_f32_e32 v21, 0x3db504f3, v33
	v_cndmask_b32_e64 v29, v20, v22, s[42:43]
	v_mul_f32_e32 v20, v88, v40
	v_cndmask_b32_e64 v33, v33, v21, s[42:43]
	v_fract_f32_e32 v21, v20
	v_cos_f32_e32 v20, v21
	v_sin_f32_e32 v21, v21
	v_mov_b32_e32 v22, v24
	v_mov_b32_e32 v34, v25
	v_mov_b32_e32 v35, v17
	v_pk_mul_f32 v[22:23], v[22:23], v[20:21]
	s_nop 0
	v_sub_f32_e32 v22, v22, v23
	v_mul_f32_e32 v23, 0x3db504f3, v22
	v_cndmask_b32_e64 v74, v22, v23, s[42:43]
	v_mul_f32_e32 v22, v89, v40
	v_fract_f32_e32 v23, v22
	v_cos_f32_e32 v22, v23
	v_sin_f32_e32 v23, v23
	s_nop 0
	v_pk_mul_f32 v[34:35], v[34:35], v[22:23]
	s_nop 0
	v_sub_f32_e32 v41, v34, v35
	v_mov_b32_e32 v34, v21
	v_mov_b32_e32 v21, v22
	v_mov_b32_e32 v35, v23
	v_pk_mul_f32 v[16:17], v[16:17], v[20:21]
	v_mul_f32_e32 v50, 0x3db504f3, v41
	v_pk_fma_f32 v[16:17], v[24:25], v[34:35], v[16:17]
	v_cndmask_b32_e64 v75, v41, v50, s[42:43]
	v_pk_mul_f32 v[20:21], v[16:17], s[12:13] op_sel_hi:[1,0]
	s_nop 0
	v_cndmask_b32_e64 v20, v16, v20, s[42:43]
	v_mul_f32_e32 v16, v56, v40
	v_cndmask_b32_e64 v21, v17, v21, s[42:43]
	v_fract_f32_e32 v17, v16
	v_cos_f32_e32 v16, v17
	v_sin_f32_e32 v17, v17
	s_nop 0
	v_pk_mul_f32 v[22:23], v[76:77], v[16:17]
	s_nop 0
	v_sub_f32_e32 v24, v22, v23
	v_mov_b32_e32 v22, v17
	v_mov_b32_e32 v23, v16
	v_pk_mul_f32 v[16:17], v[76:77], v[22:23]
	s_nop 0
	v_add_f32_e32 v16, v16, v17
	v_mul_f32_e32 v22, 0x3db504f3, v16
	v_mul_f32_e32 v17, 0x3db504f3, v24
	v_cndmask_b32_e64 v22, v16, v22, s[42:43]
	v_mul_f32_e32 v16, v57, v40
	v_cndmask_b32_e64 v76, v24, v17, s[42:43]
	v_fract_f32_e32 v17, v16
	v_cos_f32_e32 v16, v17
	v_sin_f32_e32 v17, v17
	s_nop 0
	v_pk_mul_f32 v[24:25], v[18:19], v[16:17]
	s_nop 0
	v_sub_f32_e32 v34, v24, v25
	v_mov_b32_e32 v24, v17
	v_mov_b32_e32 v25, v16
	v_pk_mul_f32 v[16:17], v[18:19], v[24:25]
	v_mov_b32_e32 v24, v13
	v_add_f32_e32 v16, v16, v17
	v_mul_f32_e32 v17, 0x3db504f3, v34
	v_cndmask_b32_e64 v77, v34, v17, s[42:43]
	v_cvt_f32_u32_e32 v34, v81
	v_mul_f32_e32 v18, 0x3db504f3, v16
	v_cndmask_b32_e64 v23, v16, v18, s[42:43]
	v_mov_b32_e32 v16, v12
	v_mul_f32_e32 v10, v10, v34
	v_fract_f32_e32 v10, v10
	v_cos_f32_e32 v18, v10
	v_sin_f32_e32 v19, v10
	v_mov_b32_e32 v17, v4
	v_mov_b32_e32 v25, v5
	v_pk_mul_f32 v[16:17], v[16:17], v[18:19]
	s_nop 0
	v_sub_f32_e32 v10, v16, v17
	v_mul_f32_e32 v16, 0x3db504f3, v10
	v_cndmask_b32_e64 v16, v10, v16, s[42:43]
	v_mul_f32_e32 v10, v11, v34
	v_fract_f32_e32 v11, v10
	v_cos_f32_e32 v10, v11
	v_sin_f32_e32 v11, v11
	s_nop 0
	v_pk_mul_f32 v[24:25], v[24:25], v[10:11]
	s_nop 0
	v_sub_f32_e32 v17, v24, v25
	v_mov_b32_e32 v24, v19
	v_mov_b32_e32 v19, v10
	v_mov_b32_e32 v25, v11
	v_pk_mul_f32 v[4:5], v[4:5], v[18:19]
	v_mul_f32_e32 v35, 0x3db504f3, v17
	v_pk_fma_f32 v[4:5], v[12:13], v[24:25], v[4:5]
	v_cndmask_b32_e64 v17, v17, v35, s[42:43]
	v_pk_mul_f32 v[10:11], v[4:5], s[12:13] op_sel_hi:[1,0]
	s_nop 0
	v_cndmask_b32_e64 v10, v4, v10, s[42:43]
; #define P (*launderP(lp))
; __device__ __forceinline__ void phase_gemm1(PREF P, int slab, char* smem) {
;     ...
;       for (int i = 0; i < 4; ++i) {
;         const int row = m0 + wm * 64 + i * 16 + l15;
;         const float s = (float)(row & ((1 << Sshift) - 1));
; #pragma unroll
;         for (int jj = 0; jj < 2; ++jj)
; #pragma unroll
;           for (int r = 0; r < 4; ++r) {
;             const int d = jj * 16 + wn * 32 + q * 4 + r;
;             float fr = __builtin_amdgcn_fractf(s * P.ropec[d]);
;             float cs = __builtin_amdgcn_cosf(fr), sn = __builtin_amdgcn_sinf(fr);
;             float t1 = acc[i][jj][r], t2 = acc[i][jj + 2][r];
;             float o1 = t1 * cs - t2 * sn, o2 = t1 * sn + t2 * cs;
;             if (region == 1) { o1 *= QK_SCALE; o2 *= QK_SCALE; }
;             acc[i][jj][r] = o1;
;             acc[i][jj + 2][r] = o2;
;           }
;       }
	v_mul_f32_e32 v4, v14, v34
	v_cndmask_b32_e64 v11, v5, v11, s[42:43]
	v_fract_f32_e32 v5, v4
	v_cos_f32_e32 v4, v5
	v_sin_f32_e32 v5, v5
	s_nop 0
	v_pk_mul_f32 v[12:13], v[84:85], v[4:5]
	s_nop 0
	v_sub_f32_e32 v14, v12, v13
	v_mov_b32_e32 v12, v5
	v_mov_b32_e32 v13, v4
	v_pk_mul_f32 v[4:5], v[84:85], v[12:13]
	s_nop 0
	v_add_f32_e32 v4, v4, v5
	v_mul_f32_e32 v12, 0x3db504f3, v4
	v_mul_f32_e32 v5, 0x3db504f3, v14
	v_cndmask_b32_e64 v12, v4, v12, s[42:43]
	v_mul_f32_e32 v4, v15, v34
	v_cndmask_b32_e64 v18, v14, v5, s[42:43]
	v_fract_f32_e32 v5, v4
	v_cos_f32_e32 v4, v5
	v_sin_f32_e32 v5, v5
	s_nop 0
	v_pk_mul_f32 v[14:15], v[6:7], v[4:5]
	s_nop 0
	v_sub_f32_e32 v19, v14, v15
	v_mov_b32_e32 v14, v5
	v_mov_b32_e32 v15, v4
	v_pk_mul_f32 v[4:5], v[6:7], v[14:15]
	v_mov_b32_e32 v7, v0
	v_add_f32_e32 v4, v4, v5
	v_mul_f32_e32 v6, 0x3db504f3, v4
	v_mul_f32_e32 v5, 0x3db504f3, v19
	v_cndmask_b32_e64 v13, v4, v6, s[42:43]
	v_mul_f32_e32 v4, v88, v34
	v_cndmask_b32_e64 v19, v19, v5, s[42:43]
	v_fract_f32_e32 v5, v4
	v_cos_f32_e32 v4, v5
	v_sin_f32_e32 v5, v5
	v_mov_b32_e32 v6, v8
	v_mov_b32_e32 v14, v9
	v_mov_b32_e32 v15, v1
	v_pk_mul_f32 v[6:7], v[6:7], v[4:5]
	s_nop 0
	v_sub_f32_e32 v6, v6, v7
	v_mul_f32_e32 v7, 0x3db504f3, v6
	v_cndmask_b32_e64 v84, v6, v7, s[42:43]
	v_mul_f32_e32 v6, v89, v34
	v_fract_f32_e32 v7, v6
	v_cos_f32_e32 v6, v7
	v_sin_f32_e32 v7, v7
	s_nop 0
	v_pk_mul_f32 v[14:15], v[14:15], v[6:7]
	s_nop 0
	v_sub_f32_e32 v24, v14, v15
	v_mov_b32_e32 v14, v5
	v_mov_b32_e32 v5, v6
	v_mov_b32_e32 v15, v7
	v_pk_mul_f32 v[0:1], v[0:1], v[4:5]
	v_mul_f32_e32 v25, 0x3db504f3, v24
	v_pk_fma_f32 v[0:1], v[8:9], v[14:15], v[0:1]
	v_cndmask_b32_e64 v85, v24, v25, s[42:43]
	v_pk_mul_f32 v[4:5], v[0:1], s[12:13] op_sel_hi:[1,0]
	s_nop 0
	v_cndmask_b32_e64 v4, v0, v4, s[42:43]
	v_mul_f32_e32 v0, v56, v34
	v_cndmask_b32_e64 v5, v1, v5, s[42:43]
	v_fract_f32_e32 v1, v0
	v_cos_f32_e32 v0, v1
	v_sin_f32_e32 v1, v1
	s_nop 0
	v_pk_mul_f32 v[6:7], v[82:83], v[0:1]
	s_nop 0
	v_sub_f32_e32 v8, v6, v7
	v_mov_b32_e32 v6, v1
	v_mov_b32_e32 v7, v0
	v_pk_mul_f32 v[0:1], v[82:83], v[6:7]
	s_nop 0
	v_add_f32_e32 v0, v0, v1
	v_mul_f32_e32 v6, 0x3db504f3, v0
	v_mul_f32_e32 v1, 0x3db504f3, v8
	v_cndmask_b32_e64 v6, v0, v6, s[42:43]
	v_mul_f32_e32 v0, v57, v34
	v_cndmask_b32_e64 v86, v8, v1, s[42:43]
	v_fract_f32_e32 v1, v0
	v_cos_f32_e32 v0, v1
	v_sin_f32_e32 v1, v1
	s_nop 0
	v_pk_mul_f32 v[8:9], v[2:3], v[0:1]
	s_nop 0
	v_sub_f32_e32 v14, v8, v9
	v_mov_b32_e32 v8, v1
	v_mov_b32_e32 v9, v0
	v_pk_mul_f32 v[0:1], v[2:3], v[8:9]
	s_nop 0
	v_add_f32_e32 v0, v0, v1
	v_mul_f32_e32 v1, 0x3db504f3, v14
	v_mul_f32_e32 v2, 0x3db504f3, v0
	v_cndmask_b32_e64 v7, v0, v2, s[42:43]
	v_cndmask_b32_e64 v87, v14, v1, s[42:43]
	v_mov_b64_e32 v[0:1], v[4:5]
	v_mov_b64_e32 v[2:3], v[6:7]
	v_mov_b64_e32 v[4:5], v[10:11]
	v_mov_b64_e32 v[6:7], v[12:13]
	v_mov_b64_e32 v[12:13], v[16:17]
	v_mov_b64_e32 v[14:15], v[18:19]
	v_mov_b64_e32 v[16:17], v[20:21]
	v_mov_b64_e32 v[18:19], v[22:23]
	v_mov_b64_e32 v[20:21], v[26:27]
	v_mov_b64_e32 v[22:23], v[28:29]
	v_mov_b64_e32 v[28:29], v[30:31]
	v_mov_b64_e32 v[30:31], v[32:33]
	v_mov_b64_e32 v[32:33], v[36:37]
	v_mov_b64_e32 v[34:35], v[38:39]
	v_mov_b64_e32 v[36:37], v[42:43]
	v_mov_b64_e32 v[38:39], v[44:45]
	v_mov_b64_e32 v[44:45], v[46:47]
	v_mov_b64_e32 v[46:47], v[48:49]
	v_mov_b64_e32 v[48:49], v[52:53]
	v_mov_b64_e32 v[50:51], v[54:55]
	v_mov_b64_e32 v[52:53], v[58:59]
	v_mov_b64_e32 v[8:9], v[84:85]
	v_mov_b64_e32 v[24:25], v[74:75]
	v_mov_b64_e32 v[40:41], v[70:71]
	v_mov_b64_e32 v[54:55], v[60:61]
	v_mov_b64_e32 v[56:57], v[66:67]
	v_mov_b64_e32 v[60:61], v[62:63]
	v_mov_b64_e32 v[10:11], v[86:87]
	v_mov_b64_e32 v[26:27], v[76:77]
	v_mov_b64_e32 v[42:43], v[72:73]
	v_mov_b64_e32 v[58:59], v[68:69]
	v_mov_b64_e32 v[62:63], v[64:65]
	s_cmp_lt_i32 s16, 3
	s_mov_b64 s[14:15], -1
	s_cbranch_scc1 .LBB0_751
	s_branch .LBB0_738
